# attention: exp of sub-tile A issued between the QK MFMAs of sub-tile B (fast path only; first/rare paths unchanged)
# speedup vs baseline: 1.0071x; 1.0071x over previous
; #define LAS __attribute__((address_space(3)))
; __device__ __forceinline__ void attn_ldk(bf16x8 (&kf)[12], const LAS unsigned char* kb) {
;     ...
;     for (int ks = 0; ks < 6; ++ks) { kf[2 * ks] = *(const LAS bf16x8*)(kb + 32 * ks); kf[2 * ks + 1] = *(const LAS bf16x8*)(kb + 32 * KP * 2 + 32 * ks); }
; }
; __device__ __forceinline__ void attn_ldv(bf16x8 (&vf)[8], const LAS unsigned char* vb) {
;     constexpr int VP = 136;
; #pragma unroll
;     for (int s = 0; s < 4; ++s) { vf[2 * s] = *(const LAS bf16x8*)(vb + 32 * s); vf[2 * s + 1] = *(const LAS bf16x8*)(vb + 32 * VP * 2 + 32 * s); }
; }
; __device__ __forceinline__ void attn_qk(f32x16& p0, f32x16& p1, const bf16x8 (&kf)[12], const bf16x8 (&qf)[6]) {
;     const f32x16 zero = {0.f, 0.f, 0.f, 0.f, 0.f, 0.f, 0.f, 0.f, 0.f, 0.f, 0.f, 0.f, 0.f, 0.f, 0.f, 0.f};
; #pragma unroll
;     for (int ks = 0; ks < 6; ++ks) {
;         p0 = __builtin_amdgcn_mfma_f32_32x32x16_bf16(kf[2 * ks], qf[ks], ks == 0 ? zero : p0, 0, 0, 0);
;         p1 = __builtin_amdgcn_mfma_f32_32x32x16_bf16(kf[2 * ks + 1], qf[ks], ks == 0 ? zero : p1, 0, 0, 0);
;     }
; }
; __device__ __forceinline__ void attn_softmax(f32x16& p0, f32x16& p1, bf16x8 (&pb)[4], f32x16& o0, f32x16& o1, float& m_run, float& l_run) {
;     float mx = max3f(p0[0], p0[1], p1[0]), my = max3f(p0[2], p0[3], p1[1]);
;     mx = max3f(mx, p1[2], p1[3]);
; #pragma unroll
;     for (int r = 4; r < 16; r += 4) { mx = max3f(mx, p0[r], p0[r + 1]); my = max3f(my, p0[r + 2], p0[r + 3]); mx = max3f(mx, p1[r], p1[r + 1]); my = max3f(my, p1[r + 2], p1[r + 3]); }
;     mx = fmaxf(mx, my);
; __device__ __forceinline__ void attn_phase(LAS unsigned char* lds, const bf16_t* __restrict__ Q, const bf16_t* __restrict__ KN, const bf16_t* __restrict__ KR,
;                                            const bf16_t* __restrict__ VT, bf16_t* AO, int vcu, int G, int tid, int lane, int wave) {
;     ...
;                 if (2 * t + 1 <= qc) {
;                     bf16x8 kf[12], kf2[12], vf[8], vf2[8], pa[4], pb2[4]; f32x16 a0, a1, b0, b1;
;                     attn_ldk(kf, kA);
;                     __builtin_amdgcn_sched_barrier(0);
;                     attn_qk(a0, a1, kf, qf);
;                     attn_ldk(kf2, kA + 64 * KP * 2);
;                     __builtin_amdgcn_sched_barrier(0);
;                     attn_qk(b0, b1, kf2, qf);
;                     attn_softmax(a0, a1, pa, o0, o1, m_run, l_run);
.Lat_both:
	v_add_u32_e32 v1, s37, v222
	v_add_u32_e32 v225, s37, v223
	ds_read_b128 v[138:141], v1
	ds_read_b128 v[142:145], v1 offset:6656
	ds_read_b128 v[146:149], v1 offset:32
	ds_read_b128 v[150:153], v1 offset:6688
	ds_read_b128 v[154:157], v1 offset:64
	ds_read_b128 v[158:161], v1 offset:6720
	ds_read_b128 v[162:165], v1 offset:96
	ds_read_b128 v[166:169], v1 offset:6752
	s_waitcnt vmcnt(5)
	s_waitcnt lgkmcnt(7)
	v_mfma_f32_32x32x16_bf16 v[34:49], v[138:141], v[114:117], v[98:113]
	ds_read_b128 v[138:141], v1 offset:128
	s_waitcnt lgkmcnt(7)
	v_mfma_f32_32x32x16_bf16 v[50:65], v[142:145], v[114:117], v[98:113]
	ds_read_b128 v[142:145], v1 offset:6784
	s_waitcnt lgkmcnt(7)
	v_mfma_f32_32x32x16_bf16 v[34:49], v[146:149], v[118:121], v[34:49]
	ds_read_b128 v[146:149], v1 offset:160
	s_waitcnt lgkmcnt(7)
	v_mfma_f32_32x32x16_bf16 v[50:65], v[150:153], v[118:121], v[50:65]
	ds_read_b128 v[150:153], v1 offset:6816
	s_waitcnt lgkmcnt(7)
	v_mfma_f32_32x32x16_bf16 v[34:49], v[154:157], v[122:125], v[34:49]
	ds_read_b128 v[154:157], v1 offset:13312
	s_waitcnt lgkmcnt(7)
	v_mfma_f32_32x32x16_bf16 v[50:65], v[158:161], v[122:125], v[50:65]
	ds_read_b128 v[158:161], v1 offset:19968
	s_waitcnt lgkmcnt(7)
	v_mfma_f32_32x32x16_bf16 v[34:49], v[162:165], v[126:129], v[34:49]
	ds_read_b128 v[162:165], v1 offset:13344
	s_waitcnt lgkmcnt(7)
	v_mfma_f32_32x32x16_bf16 v[50:65], v[166:169], v[126:129], v[50:65]
	ds_read_b128 v[166:169], v1 offset:20000
	s_waitcnt lgkmcnt(7)
	v_mfma_f32_32x32x16_bf16 v[34:49], v[138:141], v[130:133], v[34:49]
	ds_read_b128 v[138:141], v1 offset:13376
	s_waitcnt lgkmcnt(7)
	v_mfma_f32_32x32x16_bf16 v[50:65], v[142:145], v[130:133], v[50:65]
	ds_read_b128 v[142:145], v1 offset:20032
	s_waitcnt lgkmcnt(7)
	v_mfma_f32_32x32x16_bf16 v[34:49], v[146:149], v[134:137], v[34:49]
	ds_read_b128 v[146:149], v1 offset:13408
	s_waitcnt lgkmcnt(7)
	v_mfma_f32_32x32x16_bf16 v[50:65], v[150:153], v[134:137], v[50:65]
	ds_read_b128 v[150:153], v1 offset:20064
	s_cmp_lg_u32 s7, 0
	s_cbranch_scc1 .Lat_plain_A2
	s_waitcnt lgkmcnt(7)
	v_mfma_f32_32x32x16_bf16 v[66:81], v[154:157], v[114:117], v[98:113]
	ds_read_b128 v[154:157], v1 offset:13440
	s_waitcnt lgkmcnt(7)
	v_mfma_f32_32x32x16_bf16 v[82:97], v[158:161], v[114:117], v[98:113]
	ds_read_b128 v[158:161], v1 offset:20096
	s_waitcnt lgkmcnt(7)
	v_mfma_f32_32x32x16_bf16 v[66:81], v[162:165], v[118:121], v[66:81]
	ds_read_b128 v[162:165], v1 offset:13472
	v_exp_f32_e32 v34, v34
	v_exp_f32_e32 v50, v50
	v_exp_f32_e32 v35, v35
	v_exp_f32_e32 v51, v51
	s_waitcnt lgkmcnt(7)
	v_mfma_f32_32x32x16_bf16 v[82:97], v[166:169], v[118:121], v[82:97]
	ds_read_b128 v[166:169], v1 offset:20128
	v_exp_f32_e32 v36, v36
	v_exp_f32_e32 v52, v52
	v_exp_f32_e32 v37, v37
	v_exp_f32_e32 v53, v53
	s_waitcnt lgkmcnt(7)
	v_mfma_f32_32x32x16_bf16 v[66:81], v[138:141], v[122:125], v[66:81]
	ds_read_b128 v[170:173], v225 offset:26624
	v_exp_f32_e32 v38, v38
	v_exp_f32_e32 v54, v54
	v_exp_f32_e32 v39, v39
	s_waitcnt lgkmcnt(7)
	v_mfma_f32_32x32x16_bf16 v[82:97], v[142:145], v[122:125], v[82:97]
	ds_read_b128 v[174:177], v225 offset:35328
	v_exp_f32_e32 v55, v55
	v_exp_f32_e32 v40, v40
	v_exp_f32_e32 v56, v56
	s_waitcnt lgkmcnt(7)
	v_mfma_f32_32x32x16_bf16 v[66:81], v[146:149], v[126:129], v[66:81]
	ds_read_b128 v[178:181], v225 offset:26656
	v_exp_f32_e32 v41, v41
	v_exp_f32_e32 v57, v57
	v_exp_f32_e32 v42, v42
	s_waitcnt lgkmcnt(7)
	v_mfma_f32_32x32x16_bf16 v[82:97], v[150:153], v[126:129], v[82:97]
	ds_read_b128 v[182:185], v225 offset:35360
	v_exp_f32_e32 v58, v58
	v_exp_f32_e32 v43, v43
	v_exp_f32_e32 v59, v59
	s_waitcnt lgkmcnt(7)
	v_mfma_f32_32x32x16_bf16 v[66:81], v[154:157], v[130:133], v[66:81]
	ds_read_b128 v[186:189], v225 offset:26688
	v_exp_f32_e32 v44, v44
	v_exp_f32_e32 v60, v60
	v_exp_f32_e32 v45, v45
	s_waitcnt lgkmcnt(7)
	v_mfma_f32_32x32x16_bf16 v[82:97], v[158:161], v[130:133], v[82:97]
	ds_read_b128 v[190:193], v225 offset:35392
	v_exp_f32_e32 v61, v61
	v_exp_f32_e32 v46, v46
	v_exp_f32_e32 v62, v62
	s_waitcnt lgkmcnt(7)
	v_mfma_f32_32x32x16_bf16 v[66:81], v[162:165], v[134:137], v[66:81]
	v_exp_f32_e32 v47, v47
	v_exp_f32_e32 v63, v63
	v_exp_f32_e32 v48, v48
	s_waitcnt lgkmcnt(6)
	v_mfma_f32_32x32x16_bf16 v[82:97], v[166:169], v[134:137], v[82:97]
	v_exp_f32_e32 v64, v64
	v_exp_f32_e32 v49, v49
	v_exp_f32_e32 v65, v65
	s_mov_b32 s41, 0
	s_branch .Lat_sum_A2
.Lat_plain_A2:
	s_waitcnt lgkmcnt(7)
	v_mfma_f32_32x32x16_bf16 v[66:81], v[154:157], v[114:117], v[98:113]
	ds_read_b128 v[154:157], v1 offset:13440
	s_waitcnt lgkmcnt(7)
	v_mfma_f32_32x32x16_bf16 v[82:97], v[158:161], v[114:117], v[98:113]
	ds_read_b128 v[158:161], v1 offset:20096
	s_waitcnt lgkmcnt(7)
	v_mfma_f32_32x32x16_bf16 v[66:81], v[162:165], v[118:121], v[66:81]
	ds_read_b128 v[162:165], v1 offset:13472
	s_waitcnt lgkmcnt(7)
	v_mfma_f32_32x32x16_bf16 v[82:97], v[166:169], v[118:121], v[82:97]
	ds_read_b128 v[166:169], v1 offset:20128
	s_waitcnt lgkmcnt(7)
	v_mfma_f32_32x32x16_bf16 v[66:81], v[138:141], v[122:125], v[66:81]
	ds_read_b128 v[170:173], v225 offset:26624
	s_waitcnt lgkmcnt(7)
	v_mfma_f32_32x32x16_bf16 v[82:97], v[142:145], v[122:125], v[82:97]
	ds_read_b128 v[174:177], v225 offset:35328
	s_waitcnt lgkmcnt(7)
	v_mfma_f32_32x32x16_bf16 v[66:81], v[146:149], v[126:129], v[66:81]
	ds_read_b128 v[178:181], v225 offset:26656
	s_waitcnt lgkmcnt(7)
	v_mfma_f32_32x32x16_bf16 v[82:97], v[150:153], v[126:129], v[82:97]
	ds_read_b128 v[182:185], v225 offset:35360
	s_waitcnt lgkmcnt(7)
	v_mfma_f32_32x32x16_bf16 v[66:81], v[154:157], v[130:133], v[66:81]
	ds_read_b128 v[186:189], v225 offset:26688
	s_waitcnt lgkmcnt(7)
	v_mfma_f32_32x32x16_bf16 v[82:97], v[158:161], v[130:133], v[82:97]
	ds_read_b128 v[190:193], v225 offset:35392
	s_waitcnt lgkmcnt(7)
	v_mfma_f32_32x32x16_bf16 v[66:81], v[162:165], v[134:137], v[66:81]
	s_waitcnt lgkmcnt(6)
	v_mfma_f32_32x32x16_bf16 v[82:97], v[166:169], v[134:137], v[82:97]
	s_mov_b32 s41, 0
	s_cmp_lg_u32 s7, 0
	s_cbranch_scc1 .Lat_first_A2

; __device__ __forceinline__ void attn_softmax(f32x16& p0, f32x16& p1, bf16x8 (&pb)[4], f32x16& o0, f32x16& o1, float& m_run, float& l_run) {
;     ...
;     f32x16 sm = p0 + p1;
;     f32x2v s2 = (f32x2v){sm[0], sm[1]} + (f32x2v){sm[2], sm[3]};
; #pragma unroll
;     for (int r = 4; r < 16; r += 2) s2 += (f32x2v){sm[r], sm[r + 1]};
;     l_run = l_run * alpha + (s2[0] + s2[1]);
.Lat_sum_A2:
	v_pk_add_f32 v[250:251], v[34:35], v[36:37]
	v_pk_add_f32 v[252:253], v[50:51], v[52:53]
	v_pk_add_f32 v[250:251], v[250:251], v[38:39]
	v_pk_add_f32 v[252:253], v[252:253], v[54:55]
	v_pk_add_f32 v[250:251], v[250:251], v[40:41]
	v_pk_add_f32 v[252:253], v[252:253], v[56:57]
	v_pk_add_f32 v[250:251], v[250:251], v[42:43]
	v_pk_add_f32 v[252:253], v[252:253], v[58:59]
	v_pk_add_f32 v[250:251], v[250:251], v[44:45]
	v_pk_add_f32 v[252:253], v[252:253], v[60:61]
	v_pk_add_f32 v[250:251], v[250:251], v[46:47]
	v_pk_add_f32 v[252:253], v[252:253], v[62:63]
	v_pk_add_f32 v[250:251], v[250:251], v[48:49]
	v_pk_add_f32 v[252:253], v[252:253], v[64:65]
	v_pk_add_f32 v[250:251], v[250:251], v[252:253]
	v_add_f32_e32 v1, v250, v251
	v_cmp_lt_f32_e32 vcc, s26, v1
	s_cbranch_vccnz .Lat_rare_A2
